# PEER act phase: independent loads hoisted to the top of each trip, next trip's expert ids fetched one trip ahead
# baseline (speedup 1.0000x reference)
.LBB0_977:
	s_or_b64 exec, exec, s[0:1]
	s_add_u32 s14, s26, 0x19000000
	v_mov_b32_e32 v33, 0
	v_readlane_b32 s0, v246, 0
	s_addc_u32 s15, s27, 0
	v_mov_b32_e32 v201, v33
	v_readlane_b32 s1, v246, 1
	s_add_u32 s12, s26, 0x1c000000
	s_addc_u32 s13, s27, 0
	v_lshl_add_u64 v[34:35], s[0:1], 0, v[200:201]
	s_mov_b64 s[0:1], 0x200000
	v_cmp_gt_u64_e32 vcc, s[0:1], v[34:35]
	s_waitcnt lgkmcnt(0)
	s_barrier
	s_and_saveexec_b64 s[10:11], vcc
	s_cbranch_execz .LBB0_996
	v_and_b32_e32 v0, 31, v200
	v_cmp_eq_u32_e64 s[40:41], 0, v0
	v_mbcnt_lo_u32_b32 v0, -1, 0
	v_mbcnt_hi_u32_b32 v0, -1, v0
	v_and_b32_e32 v2, 64, v0
	s_add_u32 s18, s26, 0.5
	v_xor_b32_e32 v1, 16, v0
	v_add_u32_e32 v2, 64, v2
	s_addc_u32 s19, s27, 0
	v_cmp_lt_i32_e32 vcc, v1, v2
	s_lshl_b64 s[0:1], s[2:3], 12
	v_lshlrev_b32_e32 v32, 3, v200
	v_readlane_b32 s30, v246, 2
	v_cndmask_b32_e32 v0, v0, v1, vcc
	v_lshl_add_u64 v[36:37], s[0:1], 0, v[32:33]
	s_lshl_b64 s[0:1], s[2:3], 13
	v_lshlrev_b32_e32 v32, 4, v200
	v_readlane_b32 s31, v246, 3
	v_lshlrev_b32_e32 v42, 2, v0
	v_lshl_add_u64 v[0:1], s[0:1], 0, v[32:33]
	s_mov_b64 s[0:1], 0x2f000000
	s_lshl_b64 s[42:43], s[30:31], 9
	v_lshl_add_u64 v[38:39], v[0:1], 0, s[0:1]
	s_lshl_b64 s[44:45], s[30:31], 13
	s_mov_b64 s[46:47], 0
	s_mov_b32 s3, 0xffff0000
	v_mov_b32_e32 v43, 0xc0135761
	s_mov_b32 s17, 0x42ee0000
	s_mov_b32 s30, 0xf000
	v_mov_b32_e32 v44, 5
	s_mov_b64 s[58:59], 0x2d000000
	s_mov_b64 s[60:61], 0x9000000
	s_mov_b64 s[62:63], 0xa000000
	s_mov_b64 s[64:65], 0xb000000
	s_mov_b64 s[66:67], 0xc000000
	v_lshl_add_u64 v[140:141], s[26:27], 0, v[36:37]
	v_lshl_add_u64 v[140:141], v[140:141], 0, s[58:59]
	global_load_dwordx2 v[140:141], v[140:141], off
	s_branch .LBB0_980

.LBB0_980:
	v_lshl_add_u64 v[40:41], s[26:27], 0, v[36:37]
	v_lshl_add_u64 v[128:129], v[40:41], 0, s[60:61]
	global_load_dwordx2 v[128:129], v[128:129], off
	v_lshl_add_u64 v[130:131], v[40:41], 0, s[62:63]
	global_load_dwordx2 v[130:131], v[130:131], off
	v_lshl_add_u64 v[132:133], v[40:41], 0, s[64:65]
	global_load_dwordx2 v[132:133], v[132:133], off
	v_lshl_add_u64 v[134:135], v[40:41], 0, s[66:67]
	global_load_dwordx2 v[134:135], v[134:135], off
	v_lshl_add_u64 v[136:137], s[26:27], 0, v[38:39]
	global_load_dwordx4 v[136:139], v[136:137], off
	v_lshl_add_u64 v[142:143], v[40:41], 0, s[56:57]
	v_lshl_add_u64 v[142:143], v[142:143], 0, s[58:59]
	global_load_dwordx2 v[142:143], v[142:143], off
	s_mov_b32 s0, 0xa000000
	s_waitcnt vmcnt(6)
	v_mov_b32_e32 v12, v140
	v_mov_b32_e32 v13, v141
	v_lshlrev_b32_e32 v0, 5, v12
	v_lshlrev_b32_e32 v8, 5, v13
	v_and_b32_e32 v0, 0x1fffe0, v0
	v_lshlrev_b32_sdwa v4, v44, v12 dst_sel:DWORD dst_unused:UNUSED_PAD src0_sel:DWORD src1_sel:WORD_1
	v_and_b32_e32 v8, 0x1fffe0, v8
	v_lshlrev_b32_sdwa v12, v44, v13 dst_sel:DWORD dst_unused:UNUSED_PAD src0_sel:DWORD src1_sel:WORD_1
	global_load_dwordx4 v[20:23], v0, s[18:19]
	s_nop 0
	global_load_dwordx4 v[0:3], v0, s[18:19] offset:16
	s_nop 0
	global_load_dwordx4 v[16:19], v4, s[18:19]
	s_nop 0
	global_load_dwordx4 v[4:7], v4, s[18:19] offset:16
	s_nop 0
	global_load_dwordx4 v[24:27], v8, s[18:19]
	s_nop 0
	global_load_dwordx4 v[8:11], v8, s[18:19] offset:16
	s_nop 0
	global_load_dwordx4 v[28:31], v12, s[18:19]
	s_nop 0
	global_load_dwordx4 v[12:15], v12, s[18:19] offset:16
	s_waitcnt vmcnt(0)
	v_mov_b32_e32 v140, v142
	v_mov_b32_e32 v141, v143
	v_mov_b32_e32 v50, v20
	v_mov_b32_e32 v46, v128
	v_mov_b32_e32 v47, v129
	v_mov_b32_e32 v51, v16
	v_mov_b32_e32 v52, v24
	v_mov_b32_e32 v53, v28
	v_mov_b32_e32 v28, v25
	v_mov_b32_e32 v16, v21
	v_lshlrev_b32_e32 v48, 16, v46
	v_and_b32_e32 v49, 0xffff0000, v46
	v_pk_fma_f32 v[48:49], v[50:51], v[48:49], 0 op_sel_hi:[1,1,0]
	v_add_co_u32_e32 v50, vcc, s0, v40
	s_mov_b32 s0, 0xb000000
	s_nop 0
	v_addc_co_u32_e32 v51, vcc, 0, v41, vcc
	v_add_co_u32_e32 v24, vcc, s0, v40
	v_mov_b32_e32 v50, v130
	v_mov_b32_e32 v51, v131
	s_nop 0
	v_addc_co_u32_e32 v25, vcc, 0, v41, vcc
	v_mov_b32_e32 v24, v132
	v_mov_b32_e32 v25, v133
	v_lshlrev_b32_e32 v46, 16, v47
	v_and_b32_e32 v47, 0xffff0000, v47
	v_pk_fma_f32 v[46:47], v[52:53], v[46:47], 0 op_sel_hi:[1,1,0]
	s_brev_b32 s0, 48
	v_lshlrev_b32_e32 v52, 16, v50
	v_and_b32_e32 v53, 0xffff0000, v50
	v_lshlrev_b32_e32 v20, 16, v51
	v_and_b32_e32 v21, 0xffff0000, v51
	v_pk_fma_f32 v[20:21], v[28:29], v[20:21], v[46:47]
	v_pk_fma_f32 v[16:17], v[16:17], v[52:53], v[48:49]
	v_lshlrev_b32_e32 v28, 16, v24
	v_and_b32_e32 v29, 0xffff0000, v24
	v_mov_b32_e32 v46, v22
	v_mov_b32_e32 v47, v18
	v_lshlrev_b32_e32 v24, 16, v25
	v_and_b32_e32 v25, 0xffff0000, v25
	v_mov_b32_e32 v48, v26
	v_mov_b32_e32 v49, v30
	v_pk_fma_f32 v[28:29], v[46:47], v[28:29], v[16:17]
	v_pk_fma_f32 v[16:17], v[48:49], v[24:25], v[20:21]
	v_add_co_u32_e32 v20, vcc, s0, v40
	v_mov_b32_e32 v30, v27
	s_nop 0
	v_addc_co_u32_e32 v21, vcc, 0, v41, vcc
	v_mov_b32_e32 v20, v134
	v_mov_b32_e32 v21, v135
	v_mov_b32_e32 v18, v23
	v_lshlrev_b32_e32 v24, 16, v20
	v_and_b32_e32 v25, 0xffff0000, v20
	v_lshlrev_b32_e32 v20, 16, v21
	v_and_b32_e32 v21, 0xffff0000, v21
	v_pk_fma_f32 v[16:17], v[30:31], v[20:21], v[16:17]
	v_lshl_add_u64 v[20:21], s[26:27], 0, v[38:39]
	v_mov_b32_e32 v20, v136
	v_mov_b32_e32 v21, v137
	v_mov_b32_e32 v22, v138
	v_mov_b32_e32 v23, v139
	v_pk_fma_f32 v[18:19], v[18:19], v[24:25], v[28:29]
	s_nop 0
	v_mul_f32_e32 v24, v18, v18
	v_fmamk_f32 v24, v24, 0xbdd2d3e8, v43
	v_mul_f32_e32 v24, v18, v24
	v_exp_f32_e32 v24, v24
	s_nop 0
	v_add_f32_e32 v24, 1.0, v24
	v_rcp_f32_e32 v24, v24
	s_nop 0
	v_mul_f32_e32 v18, v18, v24
	v_mul_f32_e32 v20, v20, v18
	v_mul_f32_e32 v18, v19, v19
	v_fmamk_f32 v18, v18, 0xbdd2d3e8, v43
	v_mul_f32_e32 v18, v19, v18
	v_exp_f32_e32 v18, v18
	v_mul_f32_e32 v24, v0, v20
	v_add_f32_e32 v18, 1.0, v18
	v_rcp_f32_e32 v18, v18
	s_nop 0
	v_mul_f32_e32 v18, v19, v18
	v_mul_f32_e32 v21, v21, v18
	v_mul_f32_e32 v18, v16, v16
	v_fmamk_f32 v18, v18, 0xbdd2d3e8, v43
	v_mul_f32_e32 v18, v16, v18
	v_exp_f32_e32 v18, v18
	v_mul_f32_e32 v4, v4, v21
	v_max3_f32 v0, |v24|, 0, |v4|
	v_add_f32_e32 v18, 1.0, v18
	v_rcp_f32_e32 v18, v18
	s_nop 0
	v_mul_f32_e32 v16, v16, v18
	v_mul_f32_e32 v22, v22, v16
	v_mul_f32_e32 v16, v17, v17
	v_fmamk_f32 v16, v16, 0xbdd2d3e8, v43
	v_mul_f32_e32 v16, v17, v16
	v_exp_f32_e32 v16, v16
	v_mul_f32_e32 v8, v8, v22
	v_lshlrev_b32_e32 v18, 2, v34
	v_and_b32_e32 v32, 0x78, v18
	v_add_f32_e32 v16, 1.0, v16
	v_rcp_f32_e32 v16, v16
	v_lshl_add_u64 v[18:19], s[14:15], 0, v[32:33]
	v_mul_f32_e32 v16, v17, v16
	v_mul_f32_e32 v23, v23, v16
	v_mul_f32_e32 v12, v12, v23
	v_max3_f32 v0, v0, |v8|, |v12|
	v_lshrrev_b64 v[16:17], 5, v[34:35]
	s_nop 0
	v_mov_b32_dpp v25, v0 quad_perm:[1,0,3,2] row_mask:0xf bank_mask:0xf bound_ctrl:1
	v_max_f32_e32 v25, v25, v25
	v_max_f32_e32 v0, v0, v25
	s_nop 1
	v_mov_b32_dpp v25, v0 quad_perm:[2,3,0,1] row_mask:0xf bank_mask:0xf bound_ctrl:1
	v_max_f32_e32 v25, v25, v25
	v_max_f32_e32 v0, v0, v25
	s_nop 1
	v_mov_b32_dpp v25, v0 row_half_mirror row_mask:0xf bank_mask:0xf bound_ctrl:1
	v_max_f32_e32 v25, v25, v25
	v_max_f32_e32 v0, v0, v25
	s_nop 1
	v_mov_b32_dpp v25, v0 row_mirror row_mask:0xf bank_mask:0xf bound_ctrl:1
	v_max_f32_e32 v25, v25, v25
	v_max_f32_e32 v0, v0, v25
	ds_bpermute_b32 v25, v42, v0
	s_waitcnt lgkmcnt(0)
	v_max_f32_e32 v25, v25, v25
	v_max_f32_e32 v0, v0, v25
	v_div_scale_f32 v25, s[34:35], v0, v0, s17
	v_rcp_f32_e32 v26, v25
	v_cmp_lt_f32_e64 s[0:1], 0, v0
	v_fma_f32 v27, -v25, v26, 1.0
	v_fmac_f32_e32 v26, v27, v26
	v_div_scale_f32 v27, vcc, s17, v0, s17
	v_mul_f32_e32 v28, v27, v26
	v_fma_f32 v29, -v25, v28, v27
	v_fmac_f32_e32 v28, v29, v26
	v_fma_f32 v25, -v25, v28, v27
	v_div_fmas_f32 v25, v25, v26, v28
	v_div_fixup_f32 v25, v25, v0, s17
	v_cndmask_b32_e64 v25, 0, v25, s[0:1]
	v_mul_f32_e32 v24, v24, v25
	v_mul_f32_e32 v4, v4, v25
	v_mul_f32_e32 v8, v8, v25
	v_mul_f32_e32 v12, v12, v25
	v_rndne_f32_e32 v24, v24
	v_rndne_f32_e32 v4, v4
	v_rndne_f32_e32 v8, v8
	v_rndne_f32_e32 v12, v12
	v_cvt_i32_f32_e32 v24, v24
	v_cvt_i32_f32_e32 v4, v4
	v_cvt_i32_f32_e32 v8, v8
	v_cvt_i32_f32_e32 v12, v12
	v_bfe_i32 v26, v24, 0, 4
	v_bfe_i32 v27, v4, 0, 4
	v_bfe_i32 v28, v8, 0, 4
	v_bfe_i32 v25, v12, 0, 4
	v_sub_u32_e32 v26, v24, v26
	v_and_b32_e32 v24, 15, v24
	v_sub_u32_sdwa v27, v4, v27 dst_sel:WORD_1 dst_unused:UNUSED_PAD src0_sel:DWORD src1_sel:DWORD
	v_lshlrev_b32_e32 v4, 4, v4
	v_sub_u32_e32 v28, v8, v28
	v_lshlrev_b32_e32 v8, 8, v8
	v_sub_u32_sdwa v25, v12, v25 dst_sel:BYTE_3 dst_unused:UNUSED_PAD src0_sel:DWORD src1_sel:DWORD
	v_lshlrev_b32_e32 v12, 12, v12
	v_and_b32_e32 v4, 0xf0, v4
	v_and_b32_e32 v8, 0xf00, v8
	v_lshlrev_b32_e32 v28, 20, v28
	v_and_or_b32 v12, v12, s30, v24
	v_lshlrev_b32_e32 v26, 12, v26
	v_and_b32_e32 v28, 0xf000000, v28
	v_and_b32_e32 v25, 0xf0000000, v25
	v_or3_b32 v4, v12, v8, v4
	v_and_b32_e32 v26, 0xf0000, v26
	v_and_b32_e32 v27, 0xf00000, v27
	v_or3_b32 v8, v25, v28, v4
	v_or3_b32 v8, v27, v26, v8
	v_lshlrev_b64 v[24:25], 7, v[16:17]
	v_lshl_add_u64 v[18:19], v[18:19], 0, v[24:25]
	v_mov_b32_dpp v12, v8 quad_perm:[1,0,3,2] row_mask:0xf bank_mask:0xf bound_ctrl:1
	s_and_saveexec_b64 s[0:1], s[38:39]
	s_cbranch_execz .LBB0_982
	v_lshl_or_b32 v24, v12, 16, v4
	v_lshrrev_b32_e32 v4, 16, v8
	v_and_or_b32 v25, v12, s3, v4
	global_store_dwordx2 v[18:19], v[24:25], off
